# phase6 RESID_X epilogue: 64 serialized load/wait/store round trips replaced by pipelined loads with counted vmcnt
# speedup vs baseline: 1.0323x; 1.0323x over previous
.LBB0_370:
	v_or_b32_e32 v150, s10, v131
	v_add_lshl_u32 v151, v147, s11, 10
	v_add_lshl_u32 v148, v151, v150, 2
	s_mov_b32 s11, s7
	s_mov_b32 s10, s6
	global_load_dword v176, v148, s[36:37]
	global_load_dword v177, v148, s[36:37] offset:128
	v_add_u32_e32 v149, 0x1000, v148
	global_load_dword v178, v149, s[36:37]
	global_load_dword v179, v149, s[36:37] offset:128
	v_add_u32_e32 v152, 0x2000, v148
	global_load_dword v180, v152, s[36:37]
	global_load_dword v181, v152, s[36:37] offset:128
	v_add_u32_e32 v153, 0x3000, v148
	global_load_dword v182, v153, s[36:37]
	global_load_dword v183, v153, s[36:37] offset:128
	v_add_u32_e32 v154, 0x8000, v148
	global_load_dword v184, v154, s[36:37]
	global_load_dword v185, v154, s[36:37] offset:128
	v_add_u32_e32 v149, 0x9000, v148
	global_load_dword v186, v149, s[36:37]
	global_load_dword v187, v149, s[36:37] offset:128
	v_add_u32_e32 v152, 0xa000, v148
	global_load_dword v188, v152, s[36:37]
	global_load_dword v189, v152, s[36:37] offset:128
	v_add_u32_e32 v153, 0xb000, v148
	global_load_dword v190, v153, s[36:37]
	global_load_dword v191, v153, s[36:37] offset:128
	v_add_u32_e32 v154, 0x10000, v148
	global_load_dword v192, v154, s[36:37]
	global_load_dword v193, v154, s[36:37] offset:128
	v_add_u32_e32 v149, 0x11000, v148
	global_load_dword v194, v149, s[36:37]
	global_load_dword v195, v149, s[36:37] offset:128
	v_add_u32_e32 v152, 0x12000, v148
	global_load_dword v196, v152, s[36:37]
	global_load_dword v197, v152, s[36:37] offset:128
	v_add_u32_e32 v153, 0x13000, v148
	global_load_dword v198, v153, s[36:37]
	global_load_dword v199, v153, s[36:37] offset:128
	v_add_u32_e32 v154, 0x18000, v148
	global_load_dword v200, v154, s[36:37]
	global_load_dword v201, v154, s[36:37] offset:128
	v_add_u32_e32 v149, 0x19000, v148
	global_load_dword v202, v149, s[36:37]
	global_load_dword v203, v149, s[36:37] offset:128
	v_add_u32_e32 v152, 0x1a000, v148
	global_load_dword v204, v152, s[36:37]
	global_load_dword v206, v152, s[36:37] offset:128
	v_add_u32_e32 v153, 0x1b000, v148
	global_load_dword v208, v153, s[36:37]
	global_load_dword v209, v153, s[36:37] offset:128
	v_add_u32_e32 v154, 0x20000, v148
	s_waitcnt vmcnt(31)
	v_add_f32_e32 v176, v48, v176
	global_store_dword v148, v176, s[24:25]
	global_load_dword v210, v154, s[36:37]
	s_waitcnt vmcnt(32)
	v_add_f32_e32 v177, v16, v177
	global_store_dword v148, v177, s[24:25] offset:128
	global_load_dword v211, v154, s[36:37] offset:128
	v_add_u32_e32 v149, 0x1000, v148
	v_add_u32_e32 v152, 0x21000, v148
	s_waitcnt vmcnt(33)
	v_add_f32_e32 v178, v49, v178
	global_store_dword v149, v178, s[24:25]
	global_load_dword v212, v152, s[36:37]
	s_waitcnt vmcnt(34)
	v_add_f32_e32 v179, v17, v179
	global_store_dword v149, v179, s[24:25] offset:128
	global_load_dword v213, v152, s[36:37] offset:128
	v_add_u32_e32 v153, 0x2000, v148
	v_add_u32_e32 v154, 0x22000, v148
	s_waitcnt vmcnt(35)
	v_add_f32_e32 v180, v50, v180
	global_store_dword v153, v180, s[24:25]
	global_load_dword v214, v154, s[36:37]
	s_waitcnt vmcnt(36)
	v_add_f32_e32 v181, v18, v181
	global_store_dword v153, v181, s[24:25] offset:128
	global_load_dword v215, v154, s[36:37] offset:128
	v_add_u32_e32 v149, 0x3000, v148
	v_add_u32_e32 v152, 0x23000, v148
	s_waitcnt vmcnt(37)
	v_add_f32_e32 v182, v51, v182
	global_store_dword v149, v182, s[24:25]
	global_load_dword v216, v152, s[36:37]
	s_waitcnt vmcnt(38)
	v_add_f32_e32 v183, v19, v183
	global_store_dword v149, v183, s[24:25] offset:128
	global_load_dword v217, v152, s[36:37] offset:128
	v_add_u32_e32 v153, 0x8000, v148
	v_add_u32_e32 v154, 0x28000, v148
	s_waitcnt vmcnt(39)
	v_add_f32_e32 v184, v52, v184
	global_store_dword v153, v184, s[24:25]
	global_load_dword v218, v154, s[36:37]
	s_waitcnt vmcnt(40)
	v_add_f32_e32 v185, v20, v185
	global_store_dword v153, v185, s[24:25] offset:128
	global_load_dword v219, v154, s[36:37] offset:128
	v_add_u32_e32 v149, 0x9000, v148
	v_add_u32_e32 v152, 0x29000, v148
	s_waitcnt vmcnt(41)
	v_add_f32_e32 v186, v53, v186
	global_store_dword v149, v186, s[24:25]
	global_load_dword v220, v152, s[36:37]
	s_waitcnt vmcnt(42)
	v_add_f32_e32 v187, v21, v187
	global_store_dword v149, v187, s[24:25] offset:128
	global_load_dword v221, v152, s[36:37] offset:128
	v_add_u32_e32 v153, 0xa000, v148
	v_add_u32_e32 v154, 0x2a000, v148
	s_waitcnt vmcnt(43)
	v_add_f32_e32 v188, v54, v188
	global_store_dword v153, v188, s[24:25]
	global_load_dword v222, v154, s[36:37]
	s_waitcnt vmcnt(44)
	v_add_f32_e32 v189, v22, v189
	global_store_dword v153, v189, s[24:25] offset:128
	global_load_dword v223, v154, s[36:37] offset:128
	v_add_u32_e32 v149, 0xb000, v148
	v_add_u32_e32 v152, 0x2b000, v148
	s_waitcnt vmcnt(45)
	v_add_f32_e32 v190, v55, v190
	global_store_dword v149, v190, s[24:25]
	global_load_dword v224, v152, s[36:37]
	s_waitcnt vmcnt(46)
	v_add_f32_e32 v191, v23, v191
	global_store_dword v149, v191, s[24:25] offset:128
	global_load_dword v225, v152, s[36:37] offset:128
	v_add_u32_e32 v153, 0x10000, v148
	v_add_u32_e32 v154, 0x30000, v148
	s_waitcnt vmcnt(47)
	v_add_f32_e32 v192, v56, v192
	global_store_dword v153, v192, s[24:25]
	global_load_dword v226, v154, s[36:37]
	s_waitcnt vmcnt(48)
	v_add_f32_e32 v193, v24, v193
	global_store_dword v153, v193, s[24:25] offset:128
	global_load_dword v227, v154, s[36:37] offset:128
	v_add_u32_e32 v149, 0x11000, v148
	v_add_u32_e32 v152, 0x31000, v148
	s_waitcnt vmcnt(49)
	v_add_f32_e32 v194, v57, v194
	global_store_dword v149, v194, s[24:25]
	global_load_dword v228, v152, s[36:37]
	s_waitcnt vmcnt(50)
	v_add_f32_e32 v195, v25, v195
	global_store_dword v149, v195, s[24:25] offset:128
	global_load_dword v229, v152, s[36:37] offset:128
	v_add_u32_e32 v153, 0x12000, v148
	v_add_u32_e32 v154, 0x32000, v148
	s_waitcnt vmcnt(51)
	v_add_f32_e32 v196, v58, v196
	global_store_dword v153, v196, s[24:25]
	global_load_dword v230, v154, s[36:37]
	s_waitcnt vmcnt(52)
	v_add_f32_e32 v197, v26, v197
	global_store_dword v153, v197, s[24:25] offset:128
	global_load_dword v231, v154, s[36:37] offset:128
	v_add_u32_e32 v149, 0x13000, v148
	v_add_u32_e32 v152, 0x33000, v148
	s_waitcnt vmcnt(53)
	v_add_f32_e32 v198, v59, v198
	global_store_dword v149, v198, s[24:25]
	global_load_dword v232, v152, s[36:37]
	s_waitcnt vmcnt(54)
	v_add_f32_e32 v199, v27, v199
	global_store_dword v149, v199, s[24:25] offset:128
	global_load_dword v233, v152, s[36:37] offset:128
	v_add_u32_e32 v153, 0x18000, v148
	v_add_u32_e32 v154, 0x38000, v148
	s_waitcnt vmcnt(55)
	v_add_f32_e32 v200, v60, v200
	global_store_dword v153, v200, s[24:25]
	global_load_dword v234, v154, s[36:37]
	s_waitcnt vmcnt(56)
	v_add_f32_e32 v201, v28, v201
	global_store_dword v153, v201, s[24:25] offset:128
	global_load_dword v235, v154, s[36:37] offset:128
	v_add_u32_e32 v149, 0x19000, v148
	v_add_u32_e32 v152, 0x39000, v148
	s_waitcnt vmcnt(57)
	v_add_f32_e32 v202, v61, v202
	global_store_dword v149, v202, s[24:25]
	global_load_dword v170, v152, s[36:37]
	s_waitcnt vmcnt(58)
	v_add_f32_e32 v203, v29, v203
	global_store_dword v149, v203, s[24:25] offset:128
	global_load_dword v171, v152, s[36:37] offset:128
	v_add_u32_e32 v153, 0x1a000, v148
	v_add_u32_e32 v154, 0x3a000, v148
	s_waitcnt vmcnt(59)
	v_add_f32_e32 v204, v62, v204
	global_store_dword v153, v204, s[24:25]
	global_load_dword v172, v154, s[36:37]
	s_waitcnt vmcnt(60)
	v_add_f32_e32 v206, v30, v206
	global_store_dword v153, v206, s[24:25] offset:128
	global_load_dword v173, v154, s[36:37] offset:128
	v_add_u32_e32 v149, 0x1b000, v148
	v_add_u32_e32 v152, 0x3b000, v148
	s_waitcnt vmcnt(61)
	v_add_f32_e32 v208, v63, v208
	global_store_dword v149, v208, s[24:25]
	global_load_dword v174, v152, s[36:37]
	s_waitcnt vmcnt(62)
	v_add_f32_e32 v209, v31, v209
	global_store_dword v149, v209, s[24:25] offset:128
	global_load_dword v175, v152, s[36:37] offset:128
	v_add_u32_e32 v153, 0x20000, v148
	s_waitcnt vmcnt(62)
	v_add_f32_e32 v210, v32, v210
	global_store_dword v153, v210, s[24:25]
	s_waitcnt vmcnt(61)
	v_add_f32_e32 v211, v0, v211
	global_store_dword v153, v211, s[24:25] offset:128
	v_add_u32_e32 v154, 0x21000, v148
	s_waitcnt vmcnt(60)
	v_add_f32_e32 v212, v33, v212
	global_store_dword v154, v212, s[24:25]
	s_waitcnt vmcnt(59)
	v_add_f32_e32 v213, v1, v213
	global_store_dword v154, v213, s[24:25] offset:128
	v_add_u32_e32 v149, 0x22000, v148
	s_waitcnt vmcnt(58)
	v_add_f32_e32 v214, v34, v214
	global_store_dword v149, v214, s[24:25]
	s_waitcnt vmcnt(57)
	v_add_f32_e32 v215, v2, v215
	global_store_dword v149, v215, s[24:25] offset:128
	v_add_u32_e32 v152, 0x23000, v148
	s_waitcnt vmcnt(56)
	v_add_f32_e32 v216, v35, v216
	global_store_dword v152, v216, s[24:25]
	s_waitcnt vmcnt(55)
	v_add_f32_e32 v217, v3, v217
	global_store_dword v152, v217, s[24:25] offset:128
	v_add_u32_e32 v153, 0x28000, v148
	s_waitcnt vmcnt(54)
	v_add_f32_e32 v218, v36, v218
	global_store_dword v153, v218, s[24:25]
	s_waitcnt vmcnt(53)
	v_add_f32_e32 v219, v4, v219
	global_store_dword v153, v219, s[24:25] offset:128
	v_add_u32_e32 v154, 0x29000, v148
	s_waitcnt vmcnt(52)
	v_add_f32_e32 v220, v37, v220
	global_store_dword v154, v220, s[24:25]
	s_waitcnt vmcnt(51)
	v_add_f32_e32 v221, v5, v221
	global_store_dword v154, v221, s[24:25] offset:128
	v_add_u32_e32 v149, 0x2a000, v148
	s_waitcnt vmcnt(50)
	v_add_f32_e32 v222, v38, v222
	global_store_dword v149, v222, s[24:25]
	s_waitcnt vmcnt(49)
	v_add_f32_e32 v223, v6, v223
	global_store_dword v149, v223, s[24:25] offset:128
	v_add_u32_e32 v152, 0x2b000, v148
	s_waitcnt vmcnt(48)
	v_add_f32_e32 v224, v39, v224
	global_store_dword v152, v224, s[24:25]
	s_waitcnt vmcnt(47)
	v_add_f32_e32 v225, v7, v225
	global_store_dword v152, v225, s[24:25] offset:128
	v_add_u32_e32 v153, 0x30000, v148
	s_waitcnt vmcnt(46)
	v_add_f32_e32 v226, v40, v226
	global_store_dword v153, v226, s[24:25]
	s_waitcnt vmcnt(45)
	v_add_f32_e32 v227, v8, v227
	global_store_dword v153, v227, s[24:25] offset:128
	v_add_u32_e32 v154, 0x31000, v148
	s_waitcnt vmcnt(44)
	v_add_f32_e32 v228, v41, v228
	global_store_dword v154, v228, s[24:25]
	s_waitcnt vmcnt(43)
	v_add_f32_e32 v229, v9, v229
	global_store_dword v154, v229, s[24:25] offset:128
	v_add_u32_e32 v149, 0x32000, v148
	s_waitcnt vmcnt(42)
	v_add_f32_e32 v230, v42, v230
	global_store_dword v149, v230, s[24:25]
	s_waitcnt vmcnt(41)
	v_add_f32_e32 v231, v10, v231
	global_store_dword v149, v231, s[24:25] offset:128
	v_add_u32_e32 v152, 0x33000, v148
	s_waitcnt vmcnt(40)
	v_add_f32_e32 v232, v43, v232
	global_store_dword v152, v232, s[24:25]
	s_waitcnt vmcnt(39)
	v_add_f32_e32 v233, v11, v233
	global_store_dword v152, v233, s[24:25] offset:128
	v_add_u32_e32 v153, 0x38000, v148
	s_waitcnt vmcnt(38)
	v_add_f32_e32 v234, v44, v234
	global_store_dword v153, v234, s[24:25]
	s_waitcnt vmcnt(37)
	v_add_f32_e32 v235, v12, v235
	global_store_dword v153, v235, s[24:25] offset:128
	v_add_u32_e32 v154, 0x39000, v148
	s_waitcnt vmcnt(36)
	v_add_f32_e32 v170, v45, v170
	global_store_dword v154, v170, s[24:25]
	s_waitcnt vmcnt(35)
	v_add_f32_e32 v171, v13, v171
	global_store_dword v154, v171, s[24:25] offset:128
	v_add_u32_e32 v149, 0x3a000, v148
	s_waitcnt vmcnt(34)
	v_add_f32_e32 v172, v46, v172
	global_store_dword v149, v172, s[24:25]
	s_waitcnt vmcnt(33)
	v_add_f32_e32 v173, v14, v173
	global_store_dword v149, v173, s[24:25] offset:128
	v_add_u32_e32 v152, 0x3b000, v148
	s_waitcnt vmcnt(32)
	v_add_f32_e32 v174, v47, v174
	global_store_dword v152, v174, s[24:25]
	s_waitcnt vmcnt(31)
	v_add_f32_e32 v175, v15, v175
	global_store_dword v152, v175, s[24:25] offset:128
	s_andn2_b64 vcc, exec, s[4:5]
	s_cbranch_vccz .LBB0_381
